# grid barrier: the workgroup arriving half-way in its XCD issues one fire-and-forget L2 write-back so the last arriver's release finds fewer dirty lines
# baseline (speedup 1.0000x reference)
.LBB0_36:
	s_or_b64 exec, exec, s[4:5]
	v_cvt_f32_u32_e32 v4, v2
	s_waitcnt vmcnt(0)
	v_readfirstlane_b32 s0, v3
	v_sub_u32_e32 v3, 0, v2
	v_rcp_iflag_f32_e32 v4, v4
	v_add_u32_e32 v5, s0, v1
	v_mul_f32_e32 v4, 0x4f7ffffe, v4
	v_cvt_u32_f32_e32 v4, v4
	v_mul_lo_u32 v1, v3, v4
	v_mul_hi_u32 v1, v4, v1
	v_add_u32_e32 v1, v4, v1
	v_mul_hi_u32 v1, v5, v1
	v_mul_lo_u32 v3, v1, v2
	v_sub_u32_e32 v3, v5, v3
	v_add_u32_e32 v4, 1, v1
	v_cmp_ge_u32_e32 vcc, v3, v2
	s_nop 1
	v_cndmask_b32_e32 v1, v1, v4, vcc
	v_sub_u32_e32 v4, v3, v2
	v_cndmask_b32_e32 v3, v3, v4, vcc
	v_add_u32_e32 v4, 1, v1
	v_cmp_ge_u32_e32 vcc, v3, v2
	v_add_u32_e32 v3, 1, v5
	s_nop 0
	v_cndmask_b32_e32 v1, v1, v4, vcc
	v_mul_lo_u32 v4, v2, v1
	v_sub_u32_e32 v142, v5, v4
	v_lshlrev_b32_e32 v142, 1, v142
	v_cmp_eq_u32_e32 vcc, v142, v2
	s_cbranch_vccz .Lxb_noflush
	buffer_wbl2 sc1
.Lxb_noflush:
	v_add_u32_e32 v2, v4, v2
	v_cmp_ne_u32_e32 vcc, v3, v2
	s_and_saveexec_b64 s[0:1], vcc
	s_xor_b64 s[12:13], exec, s[0:1]
	s_cbranch_execz .LBB0_50
	s_waitcnt lgkmcnt(0)
	v_mov_b32_e32 v0, 0x2000
	global_load_dword v0, v0, s[10:11] offset:1024 sc1
	s_add_u32 s18, s10, 0x2400
	s_addc_u32 s19, s11, 0
	s_waitcnt vmcnt(0)
	v_cmp_eq_u32_e32 vcc, v0, v1
	s_and_saveexec_b64 s[14:15], vcc
	s_cbranch_execz .LBB0_49
	s_add_u32 s16, s8, 0x100200
	s_addc_u32 s17, s9, 0
	s_mov_b32 s4, 1
	s_mov_b64 s[20:21], 0
	s_branch .LBB0_40
